# P7 SwiGLU epilogue math repacked: per pair 3 v_pk_mul_f32 + 1 v_pk_add_f32 around the exp/rcp instead of 6 v_mul + 2 v_add (same operations and order per element)
# speedup vs baseline: 1.0076x; 1.0076x over previous
.LBB0_642:
	s_mov_b32 s98, 0xbfb8aa3b
	s_mov_b32 s99, 0xbfb8aa3b
	s_mov_b32 s100, 1.0
	s_mov_b32 s101, 1.0
	v_lshl_add_u32 v156, s65, 10, v151
	ds_read_b32 v158, v156
	v_lshl_or_b32 v146, s66, 7, v150
	v_lshl_add_u32 v155, s42, 8, v148
	v_ashrrev_i32_e32 v147, 31, v146
	v_mov_b64_e32 v[144:145], s[16:17]
	s_waitcnt lgkmcnt(0)
	v_pk_mul_f32 v[124:125], v[124:125], v[158:159] op_sel_hi:[1,0]
	v_pk_mul_f32 v[126:127], v[126:127], v[158:159] op_sel_hi:[1,0]
	v_pk_mul_f32 v[120:121], v[120:121], v[158:159] op_sel_hi:[1,0]
	v_pk_mul_f32 v[122:123], v[122:123], v[158:159] op_sel_hi:[1,0]
	v_pk_mul_f32 v[116:117], v[116:117], v[158:159] op_sel_hi:[1,0]
	v_pk_mul_f32 v[118:119], v[118:119], v[158:159] op_sel_hi:[1,0]
	v_pk_mul_f32 v[112:113], v[112:113], v[158:159] op_sel_hi:[1,0]
	v_pk_mul_f32 v[114:115], v[114:115], v[158:159] op_sel_hi:[1,0]
	v_pk_mul_f32 v[240:241], v[124:125], s[98:99] op_sel_hi:[1,0]
	v_pk_mul_f32 v[242:243], v[126:127], s[98:99] op_sel_hi:[1,0]
	v_pk_mul_f32 v[244:245], v[120:121], s[98:99] op_sel_hi:[1,0]
	v_pk_mul_f32 v[246:247], v[122:123], s[98:99] op_sel_hi:[1,0]
	v_exp_f32_e32 v240, v240
	v_exp_f32_e32 v241, v241
	v_exp_f32_e32 v242, v242
	v_exp_f32_e32 v243, v243
	v_exp_f32_e32 v244, v244
	v_exp_f32_e32 v245, v245
	v_exp_f32_e32 v246, v246
	v_exp_f32_e32 v247, v247
	v_pk_add_f32 v[240:241], v[240:241], s[100:101] op_sel_hi:[1,0]
	v_pk_add_f32 v[242:243], v[242:243], s[100:101] op_sel_hi:[1,0]
	v_pk_add_f32 v[244:245], v[244:245], s[100:101] op_sel_hi:[1,0]
	v_pk_add_f32 v[246:247], v[246:247], s[100:101] op_sel_hi:[1,0]
	v_rcp_f32_e32 v240, v240
	v_rcp_f32_e32 v241, v241
	v_rcp_f32_e32 v242, v242
	v_rcp_f32_e32 v243, v243
	v_rcp_f32_e32 v244, v244
	v_rcp_f32_e32 v245, v245
	v_rcp_f32_e32 v246, v246
	v_rcp_f32_e32 v247, v247
	v_pk_mul_f32 v[240:241], v[124:125], v[240:241]
	v_pk_mul_f32 v[242:243], v[126:127], v[242:243]
	v_pk_mul_f32 v[244:245], v[120:121], v[244:245]
	v_pk_mul_f32 v[246:247], v[122:123], v[246:247]
	v_pk_mul_f32 v[240:241], v[116:117], v[240:241]
	v_pk_mul_f32 v[242:243], v[118:119], v[242:243]
	v_pk_mul_f32 v[244:245], v[112:113], v[244:245]
	v_pk_mul_f32 v[246:247], v[114:115], v[246:247]
	v_cvt_pk_bf16_f32 v112, v240, v241
	v_cvt_pk_bf16_f32 v113, v242, v243
	v_cvt_pk_bf16_f32 v114, v244, v245
	v_cvt_pk_bf16_f32 v115, v246, v247
	v_mad_i64_i32 v[160:161], s[44:45], v155, s62, v[144:145]
	v_lshlrev_b64 v[146:147], 1, v[146:147]
	v_lshl_add_u64 v[160:161], v[160:161], 0, v[146:147]
	s_andn2_b64 vcc, exec, s[0:1]
	s_mov_b64 s[0:1], -1
	global_store_dwordx4 v[160:161], v[112:115], off
	ds_read_b32 v112, v156 offset:64
	s_nop 0
	v_or_b32_e32 v113, 16, v155
	v_mad_i64_i32 v[114:115], s[44:45], v113, s62, v[144:145]
	s_waitcnt lgkmcnt(0)
	v_pk_mul_f32 v[108:109], v[108:109], v[112:113] op_sel_hi:[1,0]
	v_pk_mul_f32 v[110:111], v[110:111], v[112:113] op_sel_hi:[1,0]
	v_pk_mul_f32 v[104:105], v[104:105], v[112:113] op_sel_hi:[1,0]
	v_pk_mul_f32 v[106:107], v[106:107], v[112:113] op_sel_hi:[1,0]
	v_pk_mul_f32 v[100:101], v[100:101], v[112:113] op_sel_hi:[1,0]
	v_pk_mul_f32 v[102:103], v[102:103], v[112:113] op_sel_hi:[1,0]
	v_pk_mul_f32 v[96:97], v[96:97], v[112:113] op_sel_hi:[1,0]
	v_pk_mul_f32 v[98:99], v[98:99], v[112:113] op_sel_hi:[1,0]
	v_pk_mul_f32 v[240:241], v[108:109], s[98:99] op_sel_hi:[1,0]
	v_pk_mul_f32 v[242:243], v[110:111], s[98:99] op_sel_hi:[1,0]
	v_pk_mul_f32 v[244:245], v[104:105], s[98:99] op_sel_hi:[1,0]
	v_pk_mul_f32 v[246:247], v[106:107], s[98:99] op_sel_hi:[1,0]
	v_exp_f32_e32 v240, v240
	v_exp_f32_e32 v241, v241
	v_exp_f32_e32 v242, v242
	v_exp_f32_e32 v243, v243
	v_exp_f32_e32 v244, v244
	v_exp_f32_e32 v245, v245
	v_exp_f32_e32 v246, v246
	v_exp_f32_e32 v247, v247
	v_pk_add_f32 v[240:241], v[240:241], s[100:101] op_sel_hi:[1,0]
	v_pk_add_f32 v[242:243], v[242:243], s[100:101] op_sel_hi:[1,0]
	v_pk_add_f32 v[244:245], v[244:245], s[100:101] op_sel_hi:[1,0]
	v_pk_add_f32 v[246:247], v[246:247], s[100:101] op_sel_hi:[1,0]
	v_rcp_f32_e32 v240, v240
	v_rcp_f32_e32 v241, v241
	v_rcp_f32_e32 v242, v242
	v_rcp_f32_e32 v243, v243
	v_rcp_f32_e32 v244, v244
	v_rcp_f32_e32 v245, v245
	v_rcp_f32_e32 v246, v246
	v_rcp_f32_e32 v247, v247
	v_pk_mul_f32 v[240:241], v[108:109], v[240:241]
	v_pk_mul_f32 v[242:243], v[110:111], v[242:243]
	v_pk_mul_f32 v[244:245], v[104:105], v[244:245]
	v_pk_mul_f32 v[246:247], v[106:107], v[246:247]
	v_pk_mul_f32 v[240:241], v[100:101], v[240:241]
	v_pk_mul_f32 v[242:243], v[102:103], v[242:243]
	v_pk_mul_f32 v[244:245], v[96:97], v[244:245]
	v_pk_mul_f32 v[246:247], v[98:99], v[246:247]
	v_cvt_pk_bf16_f32 v96, v240, v241
	v_cvt_pk_bf16_f32 v97, v242, v243
	v_cvt_pk_bf16_f32 v98, v244, v245
	v_cvt_pk_bf16_f32 v99, v246, v247
	v_lshl_add_u64 v[114:115], v[114:115], 0, v[146:147]
	global_store_dwordx4 v[114:115], v[96:99], off
	ds_read_b32 v96, v156 offset:128
	s_nop 0
	v_or_b32_e32 v97, 32, v155
	v_mad_i64_i32 v[98:99], s[44:45], v97, s62, v[144:145]
	s_waitcnt lgkmcnt(0)
	v_pk_mul_f32 v[92:93], v[92:93], v[96:97] op_sel_hi:[1,0]
	v_pk_mul_f32 v[94:95], v[94:95], v[96:97] op_sel_hi:[1,0]
	v_pk_mul_f32 v[88:89], v[88:89], v[96:97] op_sel_hi:[1,0]
	v_pk_mul_f32 v[90:91], v[90:91], v[96:97] op_sel_hi:[1,0]
	v_pk_mul_f32 v[84:85], v[84:85], v[96:97] op_sel_hi:[1,0]
	v_pk_mul_f32 v[86:87], v[86:87], v[96:97] op_sel_hi:[1,0]
	v_pk_mul_f32 v[80:81], v[80:81], v[96:97] op_sel_hi:[1,0]
	v_pk_mul_f32 v[82:83], v[82:83], v[96:97] op_sel_hi:[1,0]
	v_pk_mul_f32 v[240:241], v[92:93], s[98:99] op_sel_hi:[1,0]
	v_pk_mul_f32 v[242:243], v[94:95], s[98:99] op_sel_hi:[1,0]
	v_pk_mul_f32 v[244:245], v[88:89], s[98:99] op_sel_hi:[1,0]
	v_pk_mul_f32 v[246:247], v[90:91], s[98:99] op_sel_hi:[1,0]
	v_exp_f32_e32 v240, v240
	v_exp_f32_e32 v241, v241
	v_exp_f32_e32 v242, v242
	v_exp_f32_e32 v243, v243
	v_exp_f32_e32 v244, v244
	v_exp_f32_e32 v245, v245
	v_exp_f32_e32 v246, v246
	v_exp_f32_e32 v247, v247
	v_pk_add_f32 v[240:241], v[240:241], s[100:101] op_sel_hi:[1,0]
	v_pk_add_f32 v[242:243], v[242:243], s[100:101] op_sel_hi:[1,0]
	v_pk_add_f32 v[244:245], v[244:245], s[100:101] op_sel_hi:[1,0]
	v_pk_add_f32 v[246:247], v[246:247], s[100:101] op_sel_hi:[1,0]
	v_rcp_f32_e32 v240, v240
	v_rcp_f32_e32 v241, v241
	v_rcp_f32_e32 v242, v242
	v_rcp_f32_e32 v243, v243
	v_rcp_f32_e32 v244, v244
	v_rcp_f32_e32 v245, v245
	v_rcp_f32_e32 v246, v246
	v_rcp_f32_e32 v247, v247
	v_pk_mul_f32 v[240:241], v[92:93], v[240:241]
	v_pk_mul_f32 v[242:243], v[94:95], v[242:243]
	v_pk_mul_f32 v[244:245], v[88:89], v[244:245]
	v_pk_mul_f32 v[246:247], v[90:91], v[246:247]
	v_pk_mul_f32 v[240:241], v[84:85], v[240:241]
	v_pk_mul_f32 v[242:243], v[86:87], v[242:243]
	v_pk_mul_f32 v[244:245], v[80:81], v[244:245]
	v_pk_mul_f32 v[246:247], v[82:83], v[246:247]
	v_cvt_pk_bf16_f32 v80, v240, v241
	v_cvt_pk_bf16_f32 v81, v242, v243
	v_cvt_pk_bf16_f32 v82, v244, v245
	v_cvt_pk_bf16_f32 v83, v246, v247
	v_lshl_add_u64 v[98:99], v[98:99], 0, v[146:147]
	global_store_dwordx4 v[98:99], v[80:83], off
	ds_read_b32 v80, v156 offset:192
	s_nop 0
	v_or_b32_e32 v81, 48, v155
	v_mad_i64_i32 v[82:83], s[44:45], v81, s62, v[144:145]
	s_waitcnt lgkmcnt(0)
	v_pk_mul_f32 v[76:77], v[76:77], v[80:81] op_sel_hi:[1,0]
	v_pk_mul_f32 v[78:79], v[78:79], v[80:81] op_sel_hi:[1,0]
	v_pk_mul_f32 v[72:73], v[72:73], v[80:81] op_sel_hi:[1,0]
	v_pk_mul_f32 v[74:75], v[74:75], v[80:81] op_sel_hi:[1,0]
	v_pk_mul_f32 v[68:69], v[68:69], v[80:81] op_sel_hi:[1,0]
	v_pk_mul_f32 v[70:71], v[70:71], v[80:81] op_sel_hi:[1,0]
	v_pk_mul_f32 v[64:65], v[64:65], v[80:81] op_sel_hi:[1,0]
	v_pk_mul_f32 v[66:67], v[66:67], v[80:81] op_sel_hi:[1,0]
	v_pk_mul_f32 v[240:241], v[76:77], s[98:99] op_sel_hi:[1,0]
	v_pk_mul_f32 v[242:243], v[78:79], s[98:99] op_sel_hi:[1,0]
	v_pk_mul_f32 v[244:245], v[72:73], s[98:99] op_sel_hi:[1,0]
	v_pk_mul_f32 v[246:247], v[74:75], s[98:99] op_sel_hi:[1,0]
	v_exp_f32_e32 v240, v240
	v_exp_f32_e32 v241, v241
	v_exp_f32_e32 v242, v242
	v_exp_f32_e32 v243, v243
	v_exp_f32_e32 v244, v244
	v_exp_f32_e32 v245, v245
	v_exp_f32_e32 v246, v246
	v_exp_f32_e32 v247, v247
	v_pk_add_f32 v[240:241], v[240:241], s[100:101] op_sel_hi:[1,0]
	v_pk_add_f32 v[242:243], v[242:243], s[100:101] op_sel_hi:[1,0]
	v_pk_add_f32 v[244:245], v[244:245], s[100:101] op_sel_hi:[1,0]
	v_pk_add_f32 v[246:247], v[246:247], s[100:101] op_sel_hi:[1,0]
	v_rcp_f32_e32 v240, v240
	v_rcp_f32_e32 v241, v241
	v_rcp_f32_e32 v242, v242
	v_rcp_f32_e32 v243, v243
	v_rcp_f32_e32 v244, v244
	v_rcp_f32_e32 v245, v245
	v_rcp_f32_e32 v246, v246
	v_rcp_f32_e32 v247, v247
	v_pk_mul_f32 v[240:241], v[76:77], v[240:241]
	v_pk_mul_f32 v[242:243], v[78:79], v[242:243]
	v_pk_mul_f32 v[244:245], v[72:73], v[244:245]
	v_pk_mul_f32 v[246:247], v[74:75], v[246:247]
	v_pk_mul_f32 v[240:241], v[68:69], v[240:241]
	v_pk_mul_f32 v[242:243], v[70:71], v[242:243]
	v_pk_mul_f32 v[244:245], v[64:65], v[244:245]
	v_pk_mul_f32 v[246:247], v[66:67], v[246:247]
	v_cvt_pk_bf16_f32 v64, v240, v241
	v_cvt_pk_bf16_f32 v65, v242, v243
	v_cvt_pk_bf16_f32 v66, v244, v245
	v_cvt_pk_bf16_f32 v67, v246, v247
	v_lshl_add_u64 v[82:83], v[82:83], 0, v[146:147]
	global_store_dwordx4 v[82:83], v[64:67], off
	ds_read_b32 v64, v156 offset:512
	s_nop 0
	v_add_u32_e32 v65, 0x80, v155
	v_mad_i64_i32 v[66:67], s[44:45], v65, s62, v[144:145]
	s_waitcnt lgkmcnt(0)
	v_pk_mul_f32 v[60:61], v[60:61], v[64:65] op_sel_hi:[1,0]
	v_pk_mul_f32 v[62:63], v[62:63], v[64:65] op_sel_hi:[1,0]
	v_pk_mul_f32 v[56:57], v[56:57], v[64:65] op_sel_hi:[1,0]
	v_pk_mul_f32 v[58:59], v[58:59], v[64:65] op_sel_hi:[1,0]
	v_pk_mul_f32 v[52:53], v[52:53], v[64:65] op_sel_hi:[1,0]
	v_pk_mul_f32 v[54:55], v[54:55], v[64:65] op_sel_hi:[1,0]
	v_pk_mul_f32 v[48:49], v[48:49], v[64:65] op_sel_hi:[1,0]
	v_pk_mul_f32 v[50:51], v[50:51], v[64:65] op_sel_hi:[1,0]
	v_pk_mul_f32 v[240:241], v[60:61], s[98:99] op_sel_hi:[1,0]
	v_pk_mul_f32 v[242:243], v[62:63], s[98:99] op_sel_hi:[1,0]
	v_pk_mul_f32 v[244:245], v[56:57], s[98:99] op_sel_hi:[1,0]
	v_pk_mul_f32 v[246:247], v[58:59], s[98:99] op_sel_hi:[1,0]
	v_exp_f32_e32 v240, v240
	v_exp_f32_e32 v241, v241
	v_exp_f32_e32 v242, v242
	v_exp_f32_e32 v243, v243
	v_exp_f32_e32 v244, v244
	v_exp_f32_e32 v245, v245
	v_exp_f32_e32 v246, v246
	v_exp_f32_e32 v247, v247
	v_pk_add_f32 v[240:241], v[240:241], s[100:101] op_sel_hi:[1,0]
	v_pk_add_f32 v[242:243], v[242:243], s[100:101] op_sel_hi:[1,0]
	v_pk_add_f32 v[244:245], v[244:245], s[100:101] op_sel_hi:[1,0]
	v_pk_add_f32 v[246:247], v[246:247], s[100:101] op_sel_hi:[1,0]
	v_rcp_f32_e32 v240, v240
	v_rcp_f32_e32 v241, v241
	v_rcp_f32_e32 v242, v242
	v_rcp_f32_e32 v243, v243
	v_rcp_f32_e32 v244, v244
	v_rcp_f32_e32 v245, v245
	v_rcp_f32_e32 v246, v246
	v_rcp_f32_e32 v247, v247
	v_pk_mul_f32 v[240:241], v[60:61], v[240:241]
	v_pk_mul_f32 v[242:243], v[62:63], v[242:243]
	v_pk_mul_f32 v[244:245], v[56:57], v[244:245]
	v_pk_mul_f32 v[246:247], v[58:59], v[246:247]
	v_pk_mul_f32 v[240:241], v[52:53], v[240:241]
	v_pk_mul_f32 v[242:243], v[54:55], v[242:243]
	v_pk_mul_f32 v[244:245], v[48:49], v[244:245]
	v_pk_mul_f32 v[246:247], v[50:51], v[246:247]
	v_cvt_pk_bf16_f32 v48, v240, v241
	v_cvt_pk_bf16_f32 v49, v242, v243
	v_cvt_pk_bf16_f32 v50, v244, v245
	v_cvt_pk_bf16_f32 v51, v246, v247
	v_lshl_add_u64 v[66:67], v[66:67], 0, v[146:147]
	global_store_dwordx4 v[66:67], v[48:51], off
	ds_read_b32 v48, v156 offset:576
	s_nop 0
	v_add_u32_e32 v49, 0x90, v155
	v_mad_i64_i32 v[50:51], s[44:45], v49, s62, v[144:145]
	s_waitcnt lgkmcnt(0)
	v_pk_mul_f32 v[44:45], v[44:45], v[48:49] op_sel_hi:[1,0]
	v_pk_mul_f32 v[46:47], v[46:47], v[48:49] op_sel_hi:[1,0]
	v_pk_mul_f32 v[40:41], v[40:41], v[48:49] op_sel_hi:[1,0]
	v_pk_mul_f32 v[42:43], v[42:43], v[48:49] op_sel_hi:[1,0]
	v_pk_mul_f32 v[36:37], v[36:37], v[48:49] op_sel_hi:[1,0]
	v_pk_mul_f32 v[38:39], v[38:39], v[48:49] op_sel_hi:[1,0]
	v_pk_mul_f32 v[32:33], v[32:33], v[48:49] op_sel_hi:[1,0]
	v_pk_mul_f32 v[34:35], v[34:35], v[48:49] op_sel_hi:[1,0]
	v_pk_mul_f32 v[240:241], v[44:45], s[98:99] op_sel_hi:[1,0]
	v_pk_mul_f32 v[242:243], v[46:47], s[98:99] op_sel_hi:[1,0]
	v_pk_mul_f32 v[244:245], v[40:41], s[98:99] op_sel_hi:[1,0]
	v_pk_mul_f32 v[246:247], v[42:43], s[98:99] op_sel_hi:[1,0]
	v_exp_f32_e32 v240, v240
	v_exp_f32_e32 v241, v241
	v_exp_f32_e32 v242, v242
	v_exp_f32_e32 v243, v243
	v_exp_f32_e32 v244, v244
	v_exp_f32_e32 v245, v245
	v_exp_f32_e32 v246, v246
	v_exp_f32_e32 v247, v247
	v_pk_add_f32 v[240:241], v[240:241], s[100:101] op_sel_hi:[1,0]
	v_pk_add_f32 v[242:243], v[242:243], s[100:101] op_sel_hi:[1,0]
	v_pk_add_f32 v[244:245], v[244:245], s[100:101] op_sel_hi:[1,0]
	v_pk_add_f32 v[246:247], v[246:247], s[100:101] op_sel_hi:[1,0]
	v_rcp_f32_e32 v240, v240
	v_rcp_f32_e32 v241, v241
	v_rcp_f32_e32 v242, v242
	v_rcp_f32_e32 v243, v243
	v_rcp_f32_e32 v244, v244
	v_rcp_f32_e32 v245, v245
	v_rcp_f32_e32 v246, v246
	v_rcp_f32_e32 v247, v247
	v_pk_mul_f32 v[240:241], v[44:45], v[240:241]
	v_pk_mul_f32 v[242:243], v[46:47], v[242:243]
	v_pk_mul_f32 v[244:245], v[40:41], v[244:245]
	v_pk_mul_f32 v[246:247], v[42:43], v[246:247]
	v_pk_mul_f32 v[240:241], v[36:37], v[240:241]
	v_pk_mul_f32 v[242:243], v[38:39], v[242:243]
	v_pk_mul_f32 v[244:245], v[32:33], v[244:245]
	v_pk_mul_f32 v[246:247], v[34:35], v[246:247]
	v_cvt_pk_bf16_f32 v32, v240, v241
	v_cvt_pk_bf16_f32 v33, v242, v243
	v_cvt_pk_bf16_f32 v34, v244, v245
	v_cvt_pk_bf16_f32 v35, v246, v247
	v_lshl_add_u64 v[50:51], v[50:51], 0, v[146:147]
	global_store_dwordx4 v[50:51], v[32:35], off
	ds_read_b32 v32, v156 offset:640
	s_nop 0
	v_add_u32_e32 v33, 0xa0, v155
	v_mad_i64_i32 v[34:35], s[44:45], v33, s62, v[144:145]
	s_waitcnt lgkmcnt(0)
	v_pk_mul_f32 v[28:29], v[28:29], v[32:33] op_sel_hi:[1,0]
	v_pk_mul_f32 v[30:31], v[30:31], v[32:33] op_sel_hi:[1,0]
	v_pk_mul_f32 v[24:25], v[24:25], v[32:33] op_sel_hi:[1,0]
	v_pk_mul_f32 v[26:27], v[26:27], v[32:33] op_sel_hi:[1,0]
	v_pk_mul_f32 v[20:21], v[20:21], v[32:33] op_sel_hi:[1,0]
	v_pk_mul_f32 v[22:23], v[22:23], v[32:33] op_sel_hi:[1,0]
	v_pk_mul_f32 v[16:17], v[16:17], v[32:33] op_sel_hi:[1,0]
	v_pk_mul_f32 v[18:19], v[18:19], v[32:33] op_sel_hi:[1,0]
	v_pk_mul_f32 v[240:241], v[28:29], s[98:99] op_sel_hi:[1,0]
	v_pk_mul_f32 v[242:243], v[30:31], s[98:99] op_sel_hi:[1,0]
	v_pk_mul_f32 v[244:245], v[24:25], s[98:99] op_sel_hi:[1,0]
	v_pk_mul_f32 v[246:247], v[26:27], s[98:99] op_sel_hi:[1,0]
	v_exp_f32_e32 v240, v240
	v_exp_f32_e32 v241, v241
	v_exp_f32_e32 v242, v242
	v_exp_f32_e32 v243, v243
	v_exp_f32_e32 v244, v244
	v_exp_f32_e32 v245, v245
	v_exp_f32_e32 v246, v246
	v_exp_f32_e32 v247, v247
	v_pk_add_f32 v[240:241], v[240:241], s[100:101] op_sel_hi:[1,0]
	v_pk_add_f32 v[242:243], v[242:243], s[100:101] op_sel_hi:[1,0]
	v_pk_add_f32 v[244:245], v[244:245], s[100:101] op_sel_hi:[1,0]
	v_pk_add_f32 v[246:247], v[246:247], s[100:101] op_sel_hi:[1,0]
	v_rcp_f32_e32 v240, v240
	v_rcp_f32_e32 v241, v241
	v_rcp_f32_e32 v242, v242
	v_rcp_f32_e32 v243, v243
	v_rcp_f32_e32 v244, v244
	v_rcp_f32_e32 v245, v245
	v_rcp_f32_e32 v246, v246
	v_rcp_f32_e32 v247, v247
	v_pk_mul_f32 v[240:241], v[28:29], v[240:241]
	v_pk_mul_f32 v[242:243], v[30:31], v[242:243]
	v_pk_mul_f32 v[244:245], v[24:25], v[244:245]
	v_pk_mul_f32 v[246:247], v[26:27], v[246:247]
	v_pk_mul_f32 v[240:241], v[20:21], v[240:241]
	v_pk_mul_f32 v[242:243], v[22:23], v[242:243]
	v_pk_mul_f32 v[244:245], v[16:17], v[244:245]
	v_pk_mul_f32 v[246:247], v[18:19], v[246:247]
	v_cvt_pk_bf16_f32 v16, v240, v241
	v_cvt_pk_bf16_f32 v17, v242, v243
	v_cvt_pk_bf16_f32 v18, v244, v245
	v_cvt_pk_bf16_f32 v19, v246, v247
	v_lshl_add_u64 v[34:35], v[34:35], 0, v[146:147]
	global_store_dwordx4 v[34:35], v[16:19], off
	ds_read_b32 v16, v156 offset:704
	s_nop 0
	v_add_u32_e32 v17, 0xb0, v155
	v_mad_i64_i32 v[18:19], s[44:45], v17, s62, v[144:145]
	s_waitcnt lgkmcnt(0)
	v_pk_mul_f32 v[12:13], v[12:13], v[16:17] op_sel_hi:[1,0]
	v_pk_mul_f32 v[14:15], v[14:15], v[16:17] op_sel_hi:[1,0]
	v_pk_mul_f32 v[8:9], v[8:9], v[16:17] op_sel_hi:[1,0]
	v_pk_mul_f32 v[10:11], v[10:11], v[16:17] op_sel_hi:[1,0]
	v_pk_mul_f32 v[4:5], v[4:5], v[16:17] op_sel_hi:[1,0]
	v_pk_mul_f32 v[6:7], v[6:7], v[16:17] op_sel_hi:[1,0]
	v_pk_mul_f32 v[0:1], v[0:1], v[16:17] op_sel_hi:[1,0]
	v_pk_mul_f32 v[2:3], v[2:3], v[16:17] op_sel_hi:[1,0]
	v_pk_mul_f32 v[240:241], v[12:13], s[98:99] op_sel_hi:[1,0]
	v_pk_mul_f32 v[242:243], v[14:15], s[98:99] op_sel_hi:[1,0]
	v_pk_mul_f32 v[244:245], v[8:9], s[98:99] op_sel_hi:[1,0]
	v_pk_mul_f32 v[246:247], v[10:11], s[98:99] op_sel_hi:[1,0]
	v_exp_f32_e32 v240, v240
	v_exp_f32_e32 v241, v241
	v_exp_f32_e32 v242, v242
	v_exp_f32_e32 v243, v243
	v_exp_f32_e32 v244, v244
	v_exp_f32_e32 v245, v245
	v_exp_f32_e32 v246, v246
	v_exp_f32_e32 v247, v247
	v_pk_add_f32 v[240:241], v[240:241], s[100:101] op_sel_hi:[1,0]
	v_pk_add_f32 v[242:243], v[242:243], s[100:101] op_sel_hi:[1,0]
	v_pk_add_f32 v[244:245], v[244:245], s[100:101] op_sel_hi:[1,0]
	v_pk_add_f32 v[246:247], v[246:247], s[100:101] op_sel_hi:[1,0]
	v_rcp_f32_e32 v240, v240
	v_rcp_f32_e32 v241, v241
	v_rcp_f32_e32 v242, v242
	v_rcp_f32_e32 v243, v243
	v_rcp_f32_e32 v244, v244
	v_rcp_f32_e32 v245, v245
	v_rcp_f32_e32 v246, v246
	v_rcp_f32_e32 v247, v247
	v_pk_mul_f32 v[240:241], v[12:13], v[240:241]
	v_pk_mul_f32 v[242:243], v[14:15], v[242:243]
	v_pk_mul_f32 v[244:245], v[8:9], v[244:245]
	v_pk_mul_f32 v[246:247], v[10:11], v[246:247]
	v_pk_mul_f32 v[240:241], v[4:5], v[240:241]
	v_pk_mul_f32 v[242:243], v[6:7], v[242:243]
	v_pk_mul_f32 v[244:245], v[0:1], v[244:245]
	v_pk_mul_f32 v[246:247], v[2:3], v[246:247]
	v_cvt_pk_bf16_f32 v0, v240, v241
	v_cvt_pk_bf16_f32 v1, v242, v243
	v_cvt_pk_bf16_f32 v2, v244, v245
	v_cvt_pk_bf16_f32 v3, v246, v247
	v_lshl_add_u64 v[18:19], v[18:19], 0, v[146:147]
	global_store_dwordx4 v[18:19], v[0:3], off
	s_cbranch_vccnz .LBB0_635
	s_andn2_b64 vcc, exec, s[4:5]
	s_cbranch_vccnz .LBB0_634
	s_barrier
	s_branch .LBB0_634
